# GEMM first-unit prologue: the second group of K-tile loads is issued before waiting for the first group (the wait/barrier pair moves below it, vmcnt 2 -> 8), so the two cold round trips overlap
# baseline (speedup 1.0000x reference)
.LBB0_346:
	s_mov_b64 s[26:27], 0x80
	s_add_i32 m0, s23, 0x18000
	v_lshl_add_u64 v[10:11], v[10:11], 0, s[26:27]
	global_load_lds_dwordx4 v[10:11], off
	v_lshl_add_u64 v[6:7], v[6:7], 0, s[26:27]
	s_add_i32 m0, s23, 0x1a000
	s_add_i32 s97, s23, 0x8000
	global_load_lds_dwordx4 v[6:7], off
	v_lshl_add_u64 v[6:7], v[8:9], 0, s[26:27]
	s_mov_b32 m0, s97
	s_add_i32 s89, s23, 0xa000
	global_load_lds_dwordx4 v[6:7], off
	v_lshl_add_u64 v[6:7], v[12:13], 0, s[26:27]
	s_mov_b32 m0, s89
	v_lshl_add_u64 v[4:5], v[4:5], 0, s[26:27]
	global_load_lds_dwordx4 v[6:7], off
	s_add_i32 m0, s23, 0x1c000
	v_lshl_add_u64 v[2:3], v[2:3], 0, s[26:27]
	global_load_lds_dwordx4 v[4:5], off
	s_add_i32 m0, s23, 0x1e000
	s_and_b32 s95, s0, 3
	global_load_lds_dwordx4 v[2:3], off
	s_waitcnt vmcnt(8)
	s_barrier
	v_bfe_u32 v21, v14, 4, 2
	s_lshr_b32 s0, s13, 26
	v_and_b32_e32 v1, 15, v14
	s_add_i32 s0, s12, s0
	v_lshlrev_b32_e32 v22, 4, v21
	v_lshlrev_b32_e32 v3, 2, v14
	s_ashr_i32 s74, s0, 6
	v_lshl_or_b32 v2, v1, 6, v22
	s_lshl_b32 s0, s1, 13
	v_and_b32_e32 v3, 32, v3
	s_lshl_b32 s96, s1, 6
	v_bitop3_b32 v4, v2, s0, v3 bitop3:0xde
	s_lshl_b32 s88, s95, 5
	s_lshl_b32 s0, s95, 12
	v_bitop3_b32 v145, v2, s0, v3 bitop3:0xde
	s_mov_b32 s0, s12
	s_cmp_gt_i32 s12, 63
	v_writelane_b32 v251, s0, 5
	s_cselect_b64 s[28:29], -1, 0
	s_add_i32 s87, s74, -2
	v_writelane_b32 v251, s1, 6
	s_cmpk_lt_u32 s3, 0x100
	v_cmp_gt_u32_e64 s[0:1], 2, v21
	s_cselect_b64 s[34:35], -1, 0
	s_cmp_eq_u32 s95, 0
	v_writelane_b32 v251, s0, 57
	s_cselect_b64 s[36:37], -1, 0
	s_or_b32 s75, s88, 0x80
	v_writelane_b32 v251, s1, 58
	s_add_i32 s0, s96, 0xfffffd00
	s_add_u32 s38, s80, 0x1140000
	s_addc_u32 s39, s81, 0
	v_or_b32_e32 v147, s0, v1
	s_add_u32 s0, s80, 0x6900000
	s_addc_u32 s1, s81, 0
	v_writelane_b32 v251, s0, 59
	v_lshlrev_b32_e32 v23, 3, v21
	v_or_b32_e32 v144, s88, v23
	v_writelane_b32 v251, s1, 60
	s_add_u32 s0, s80, 0x3f00000
	s_addc_u32 s1, s81, 0
	s_add_u32 s12, s80, 0x4700000
	s_addc_u32 s13, s81, 0
	s_add_u32 s14, s80, 0x3600000
	s_addc_u32 s15, s81, 0
	s_add_u32 s42, s80, 0x1200000
	v_and_b32_e32 v2, 16, v14
	v_bitop3_b32 v146, s88, 56, v23 bitop3:0xc8
	v_bitop3_b32 v148, s75, 56, v23 bitop3:0xc8
	v_lshlrev_b32_e32 v142, 1, v144
	s_addc_u32 s43, s81, 0
	v_cmp_eq_u32_e64 s[4:5], 0, v2
	v_or_b32_e32 v5, s75, v23
	v_lshl_add_u64 v[150:151], s[0:1], 0, v[142:143]
	v_lshlrev_b32_e32 v2, 1, v146
	v_mov_b32_e32 v3, v143
	v_lshl_add_u64 v[154:155], s[14:15], 0, v[142:143]
	v_lshlrev_b32_e32 v142, 1, v148
	s_add_u32 s44, s80, 0x1180000
	v_lshl_add_u64 v[152:153], s[12:13], 0, v[2:3]
	v_lshl_add_u64 v[156:157], s[12:13], 0, v[142:143]
	s_addc_u32 s45, s81, 0
	v_lshlrev_b32_e32 v142, 1, v5
	v_add_u32_e32 v2, v17, v15
	s_waitcnt vmcnt(6)
	s_add_u32 s46, s80, 0x5800000
	v_lshl_add_u64 v[158:159], s[0:1], 0, v[142:143]
	v_lshl_add_u64 v[160:161], s[14:15], 0, v[142:143]
	v_add_lshl_u32 v142, v2, v16, 1
	v_add_u32_e32 v2, v20, v18
	s_addc_u32 s47, s81, 0
	v_mov_b32_e32 v23, v143
	v_lshl_add_u64 v[164:165], s[20:21], 0, v[142:143]
	v_add_lshl_u32 v142, v2, v19, 1
	s_add_i32 s86, 0, 0x10000
	s_add_i32 s33, 0, 0x14000
	v_mbcnt_lo_u32_b32 v2, -1, 0
	v_cmp_eq_u32_e64 s[6:7], 0, v21
	v_or_b32_e32 v149, 0x1000, v144
	v_lshl_add_u64 v[162:163], s[78:79], 0, v[22:23]
	v_lshl_add_u64 v[166:167], s[20:21], 0, v[142:143]
	v_add_u32_e32 v188, 0, v4
	s_movk_i32 s16, 0x3fff
	s_mov_b32 s48, 0x3e38aa3b
	s_movk_i32 s18, 0x1100
	s_movk_i32 s19, 0x2200
	v_add_u32_e32 v189, s86, v145
	v_add_u32_e32 v190, s33, v145
	v_mbcnt_hi_u32_b32 v191, -1, v2
	v_mov_b32_e32 v192, 0xf78
	s_barrier
	s_branch .LBB0_349

.LBB0_860:
	s_mov_b64 s[30:31], 0x80
	s_add_i32 m0, s27, 0x18000
	v_lshl_add_u64 v[10:11], v[10:11], 0, s[30:31]
	global_load_lds_dwordx4 v[10:11], off
	v_lshl_add_u64 v[6:7], v[6:7], 0, s[30:31]
	s_add_i32 m0, s27, 0x1a000
	s_add_i32 s74, s27, 0x8000
	global_load_lds_dwordx4 v[6:7], off
	v_lshl_add_u64 v[6:7], v[8:9], 0, s[30:31]
	s_mov_b32 m0, s74
	s_add_i32 s75, s27, 0xa000
	global_load_lds_dwordx4 v[6:7], off
	v_lshl_add_u64 v[6:7], v[12:13], 0, s[30:31]
	s_mov_b32 m0, s75
	v_lshl_add_u64 v[4:5], v[4:5], 0, s[30:31]
	global_load_lds_dwordx4 v[6:7], off
	s_add_i32 m0, s27, 0x1c000
	v_lshl_add_u64 v[2:3], v[2:3], 0, s[30:31]
	global_load_lds_dwordx4 v[4:5], off
	s_add_i32 m0, s27, 0x1e000
	s_and_b32 s89, s0, 3
	global_load_lds_dwordx4 v[2:3], off
	s_waitcnt vmcnt(8)
	s_barrier
	v_bfe_u32 v21, v14, 4, 2
	s_lshr_b32 s0, s13, 26
	v_and_b32_e32 v1, 15, v14
	s_add_i32 s0, s12, s0
	v_lshlrev_b32_e32 v22, 4, v21
	v_lshlrev_b32_e32 v3, 2, v14
	s_ashr_i32 s22, s0, 6
	v_lshl_or_b32 v2, v1, 6, v22
	s_lshl_b32 s0, s1, 13
	v_and_b32_e32 v3, 32, v3
	s_lshl_b32 s88, s1, 6
	v_bitop3_b32 v4, v2, s0, v3 bitop3:0xde
	s_lshl_b32 s86, s89, 5
	s_lshl_b32 s0, s89, 12
	v_bitop3_b32 v145, v2, s0, v3 bitop3:0xde
	s_mov_b32 s0, s12
	s_cmp_gt_i32 s12, 63
	v_writelane_b32 v251, s0, 5
	s_cselect_b64 s[36:37], -1, 0
	s_add_i32 s87, s22, -2
	v_writelane_b32 v251, s1, 6
	s_cmpk_lt_u32 s3, 0x100
	v_cmp_gt_u32_e64 s[0:1], 2, v21
	s_cselect_b64 s[38:39], -1, 0
	s_cmp_eq_u32 s89, 0
	v_writelane_b32 v251, s0, 57
	s_cselect_b64 s[40:41], -1, 0
	s_or_b32 s23, s86, 0x80
	v_writelane_b32 v251, s1, 58
	s_add_i32 s0, s88, 0xfffffd00
	s_add_u32 s42, s80, 0x1140000
	s_addc_u32 s43, s81, 0
	v_or_b32_e32 v147, s0, v1
	s_add_u32 s0, s80, 0x6900000
	s_addc_u32 s1, s81, 0
	v_writelane_b32 v251, s0, 59
	v_lshlrev_b32_e32 v23, 3, v21
	v_or_b32_e32 v144, s86, v23
	v_writelane_b32 v251, s1, 60
	s_add_u32 s0, s80, 0x3f00000
	s_addc_u32 s1, s81, 0
	s_add_u32 s12, s80, 0x4700000
	s_addc_u32 s13, s81, 0
	s_add_u32 s14, s80, 0x3600000
	s_addc_u32 s15, s81, 0
	s_add_u32 s46, s80, 0x1200000
	v_and_b32_e32 v2, 16, v14
	v_bitop3_b32 v146, s86, 56, v23 bitop3:0xc8
	v_bitop3_b32 v148, s23, 56, v23 bitop3:0xc8
	v_lshlrev_b32_e32 v142, 1, v144
	s_addc_u32 s47, s81, 0
	v_cmp_eq_u32_e64 s[4:5], 0, v2
	v_or_b32_e32 v5, s23, v23
	v_lshl_add_u64 v[150:151], s[0:1], 0, v[142:143]
	v_lshlrev_b32_e32 v2, 1, v146
	v_mov_b32_e32 v3, v143
	v_lshl_add_u64 v[154:155], s[14:15], 0, v[142:143]
	v_lshlrev_b32_e32 v142, 1, v148
	s_add_u32 s48, s80, 0x1180000
	v_lshl_add_u64 v[152:153], s[12:13], 0, v[2:3]
	v_lshl_add_u64 v[156:157], s[12:13], 0, v[142:143]
	s_addc_u32 s49, s81, 0
	v_lshlrev_b32_e32 v142, 1, v5
	v_add_u32_e32 v2, v17, v15
	s_waitcnt vmcnt(6)
	s_add_u32 s50, s80, 0x5800000
	v_lshl_add_u64 v[158:159], s[0:1], 0, v[142:143]
	v_lshl_add_u64 v[160:161], s[14:15], 0, v[142:143]
	v_add_lshl_u32 v142, v2, v16, 1
	v_add_u32_e32 v2, v20, v18
	s_addc_u32 s51, s81, 0
	v_mov_b32_e32 v23, v143
	v_lshl_add_u64 v[164:165], s[24:25], 0, v[142:143]
	v_add_lshl_u32 v142, v2, v19, 1
	s_add_i32 s16, 0, 0x10000
	s_add_i32 s19, 0, 0x14000
	v_mbcnt_lo_u32_b32 v2, -1, 0
	v_cmp_eq_u32_e64 s[6:7], 0, v21
	v_or_b32_e32 v149, 0x1000, v144
	v_lshl_add_u64 v[162:163], s[78:79], 0, v[22:23]
	v_lshl_add_u64 v[166:167], s[24:25], 0, v[142:143]
	v_add_u32_e32 v188, 0, v4
	s_movk_i32 s33, 0x3fff
	s_mov_b32 s52, 0x3e38aa3b
	s_movk_i32 s18, 0x1100
	s_movk_i32 s0, 0x2200
	v_add_u32_e32 v189, s16, v145
	v_add_u32_e32 v190, s19, v145
	v_mbcnt_hi_u32_b32 v191, -1, v2
	v_mov_b32_e32 v192, 0xf78
	s_barrier
	s_branch .LBB0_863

.LBB0_1325:
	s_mov_b64 s[22:23], 0x80
	s_add_i32 m0, s18, 0x18000
	v_lshl_add_u64 v[10:11], v[10:11], 0, s[22:23]
	global_load_lds_dwordx4 v[10:11], off
	v_lshl_add_u64 v[6:7], v[6:7], 0, s[22:23]
	s_add_i32 m0, s18, 0x1a000
	s_add_i32 s57, s18, 0x8000
	global_load_lds_dwordx4 v[6:7], off
	v_lshl_add_u64 v[6:7], v[8:9], 0, s[22:23]
	s_mov_b32 m0, s57
	s_add_i32 s58, s18, 0xa000
	global_load_lds_dwordx4 v[6:7], off
	v_lshl_add_u64 v[6:7], v[12:13], 0, s[22:23]
	s_mov_b32 m0, s58
	v_lshl_add_u64 v[4:5], v[4:5], 0, s[22:23]
	global_load_lds_dwordx4 v[6:7], off
	s_add_i32 m0, s18, 0x1c000
	v_lshl_add_u64 v[2:3], v[2:3], 0, s[22:23]
	global_load_lds_dwordx4 v[4:5], off
	s_add_i32 m0, s18, 0x1e000
	s_and_b32 s60, s0, 3
	global_load_lds_dwordx4 v[2:3], off
	s_waitcnt vmcnt(8)
	s_barrier
	v_bfe_u32 v3, v14, 4, 2
	s_lshr_b32 s0, s73, 26
	v_and_b32_e32 v1, 15, v14
	s_add_i32 s0, s72, s0
	v_lshlrev_b32_e32 v2, 4, v3
	v_lshlrev_b32_e32 v6, 2, v14
	s_ashr_i32 s61, s0, 6
	v_lshl_or_b32 v5, v1, 6, v2
	s_lshl_b32 s0, s1, 13
	v_and_b32_e32 v6, 32, v6
	s_sub_i32 s59, s88, s2
	s_lshl_b32 s62, s1, 6
	v_bitop3_b32 v7, v5, s0, v6 bitop3:0xde
	s_lshl_b32 s63, s60, 5
	s_lshl_b32 s0, s60, 12
	s_cmp_gt_i32 s72, 63
	s_cselect_b64 s[24:25], -1, 0
	s_add_i32 s64, s61, -2
	s_cmpk_lt_u32 s4, 0x100
	s_cselect_b64 s[26:27], -1, 0
	s_add_u32 s28, s80, 0x1200000
	s_addc_u32 s29, s81, 0
	v_lshlrev_b32_e32 v4, 3, v3
	s_add_u32 s30, s80, 0x1140000
	v_bitop3_b32 v166, v5, s0, v6 bitop3:0xde
	s_addc_u32 s31, s81, 0
	v_and_or_b32 v5, s63, 32, v4
	v_cmp_gt_u32_e64 s[0:1], 2, v3
	v_lshlrev_b32_e32 v170, 6, v3
	v_mov_b32_e32 v3, v139
	v_lshlrev_b32_e32 v138, 1, v5
	s_add_u32 s34, s80, 0x1180000
	v_lshl_add_u64 v[144:145], s[20:21], 0, v[2:3]
	v_add_u32_e32 v2, v17, v15
	v_lshl_add_u64 v[140:141], s[78:79], 0, v[138:139]
	s_addc_u32 s35, s81, 0
	v_lshl_add_u64 v[142:143], s[20:21], 0, v[138:139]
	v_add_lshl_u32 v138, v2, v16, 1
	v_add_u32_e32 v2, v20, v18
	s_waitcnt vmcnt(6)
	s_add_u32 s36, s78, 0x1a00000
	v_lshl_add_u64 v[146:147], s[12:13], 0, v[138:139]
	v_add_lshl_u32 v138, v2, v19, 1
	v_cndmask_b32_e64 v2, 0, 1, s[6:7]
	v_and_b32_e32 v6, 16, v14
	s_addc_u32 s37, s79, 0
	v_or_b32_e32 v167, s63, v4
	v_cmp_ne_u32_e64 s[6:7], 1, v2
	s_add_i32 s68, 0, 0x10000
	s_add_i32 s69, 0, 0x14000
	v_mbcnt_lo_u32_b32 v2, -1, 0
	s_mov_b32 s92, s72
	v_cmp_eq_u32_e64 s[4:5], 0, v6
	v_and_b32_e32 v168, 7, v14
	s_add_i32 s65, s62, 0xfffffe00
	s_movk_i32 s66, 0x1000
	v_or_b32_e32 v169, 0x1000, v167
	s_sub_i32 s67, s86, s2
	v_or_b32_e32 v171, 0x80, v1
	v_lshl_add_u64 v[148:149], s[12:13], 0, v[138:139]
	v_add_u32_e32 v172, s68, v166
	v_add_u32_e32 v173, s69, v166
	v_add_u32_e32 v174, 0, v7
	s_movk_i32 s70, 0x3fff
	v_mov_b32_e32 v175, 0x358637bd
	s_mov_b32 s71, 0xf800000
	v_mov_b32_e32 v176, 0x260
	s_movk_i32 s72, 0x1100
	s_mov_b32 s73, 0x3e16c740
	s_movk_i32 s74, 0x2200
	v_mbcnt_hi_u32_b32 v177, -1, v2
	v_mov_b32_e32 v178, 0xf78
	s_barrier
	s_branch .LBB0_1328

.LBB0_1546:
	s_mov_b64 s[14:15], 0x80
	s_add_i32 m0, s29, 0x18000
	v_lshl_add_u64 v[12:13], v[12:13], 0, s[14:15]
	global_load_lds_dwordx4 v[12:13], off
	v_lshl_add_u64 v[8:9], v[8:9], 0, s[14:15]
	s_add_i32 m0, s29, 0x1a000
	s_add_i32 s58, s29, 0x8000
	global_load_lds_dwordx4 v[8:9], off
	v_lshl_add_u64 v[8:9], v[10:11], 0, s[14:15]
	s_mov_b32 m0, s58
	s_add_i32 s59, s29, 0xa000
	global_load_lds_dwordx4 v[8:9], off
	v_lshl_add_u64 v[6:7], v[6:7], 0, s[14:15]
	s_mov_b32 m0, s59
	v_lshl_add_u64 v[4:5], v[4:5], 0, s[14:15]
	global_load_lds_dwordx4 v[6:7], off
	s_add_i32 m0, s29, 0x1c000
	v_lshl_add_u64 v[2:3], v[2:3], 0, s[14:15]
	global_load_lds_dwordx4 v[4:5], off
	s_add_i32 m0, s29, 0x1e000
	s_and_b32 s60, s0, 3
	global_load_lds_dwordx4 v[2:3], off
	s_waitcnt vmcnt(8)
	s_barrier
	v_bfe_u32 v3, v14, 4, 2
	s_lshr_b32 s0, s73, 26
	v_and_b32_e32 v1, 15, v14
	s_add_i32 s0, s72, s0
	v_lshlrev_b32_e32 v2, 4, v3
	v_lshlrev_b32_e32 v6, 2, v14
	s_ashr_i32 s61, s0, 6
	v_lshl_or_b32 v5, v1, 6, v2
	s_lshl_b32 s0, s1, 13
	v_and_b32_e32 v6, 32, v6
	s_lshl_b32 s62, s1, 6
	v_bitop3_b32 v7, v5, s0, v6 bitop3:0xde
	s_lshl_b32 s63, s60, 5
	s_lshl_b32 s0, s60, 12
	s_cmp_gt_i32 s72, 63
	s_cselect_b64 s[16:17], -1, 0
	s_add_i32 s64, s61, -2
	s_cmpk_lt_u32 s3, 0x100
	s_cselect_b64 s[18:19], -1, 0
	s_add_u32 s20, s80, 0x1200000
	s_addc_u32 s21, s81, 0
	s_add_u32 s22, s80, 0x1140000
	s_addc_u32 s23, s81, 0
	s_add_u32 s24, s80, 0x1180000
	s_addc_u32 s25, s81, 0
	v_lshlrev_b32_e32 v4, 3, v3
	s_add_u32 s30, s80, 0x1400000
	v_bitop3_b32 v166, v5, s0, v6 bitop3:0xde
	v_and_or_b32 v5, s63, 32, v4
	v_cmp_gt_u32_e64 s[0:1], 2, v3
	s_addc_u32 s31, s81, 0
	v_lshlrev_b32_e32 v170, 6, v3
	v_mov_b32_e32 v3, v139
	v_lshlrev_b32_e32 v138, 1, v5
	v_lshl_add_u64 v[144:145], s[30:31], 0, v[2:3]
	v_add_u32_e32 v2, v17, v15
	s_waitcnt vmcnt(6)
	v_lshl_add_u64 v[140:141], s[78:79], 0, v[138:139]
	v_lshl_add_u64 v[142:143], s[30:31], 0, v[138:139]
	s_add_u32 s26, s78, 0x1a00000
	v_add_lshl_u32 v138, v2, v16, 1
	v_add_u32_e32 v2, v20, v18
	v_and_b32_e32 v6, 16, v14
	s_addc_u32 s27, s79, 0
	v_or_b32_e32 v167, s63, v4
	v_lshl_add_u64 v[146:147], s[10:11], 0, v[138:139]
	v_add_lshl_u32 v138, v2, v19, 1
	s_add_i32 s68, 0, 0x10000
	s_add_i32 s69, 0, 0x14000
	v_mbcnt_lo_u32_b32 v2, -1, 0
	s_movk_i32 s65, 0x100
	v_cmp_eq_u32_e64 s[4:5], 0, v6
	v_and_b32_e32 v168, 7, v14
	s_add_i32 s66, s62, 0xfffffe00
	s_movk_i32 s67, 0x1000
	v_or_b32_e32 v169, 0x1000, v167
	v_or_b32_e32 v171, 0x80, v1
	v_lshl_add_u64 v[148:149], s[10:11], 0, v[138:139]
	v_add_u32_e32 v172, s68, v166
	v_add_u32_e32 v173, s69, v166
	v_add_u32_e32 v174, 0, v7
	s_movk_i32 s70, 0x3fff
	v_mov_b32_e32 v175, 0x358637bd
	s_mov_b32 s71, 0xf800000
	v_mov_b32_e32 v176, 0x260
	s_movk_i32 s72, 0x1100
	s_mov_b32 s73, 0x3e16c740
	s_movk_i32 s74, 0x2200
	v_mbcnt_hi_u32_b32 v177, -1, v2
	v_mov_b32_e32 v178, 0xf78
	s_barrier
	s_branch .LBB0_1549

.LBB0_1980:
	s_add_u32 s49, s80, 0x8900000
	s_addc_u32 s50, s81, 0
	s_add_u32 s51, s80, 0xe00000
	s_mov_b64 s[14:15], 0x80
	s_addc_u32 s52, s81, 0
	s_add_i32 m0, s45, 0x18000
	v_lshl_add_u64 v[12:13], v[12:13], 0, s[14:15]
	global_load_lds_dwordx4 v[12:13], off
	v_lshl_add_u64 v[8:9], v[8:9], 0, s[14:15]
	s_add_i32 m0, s45, 0x1a000
	s_add_i32 s54, s45, 0x8000
	global_load_lds_dwordx4 v[8:9], off
	v_lshl_add_u64 v[8:9], v[10:11], 0, s[14:15]
	s_mov_b32 m0, s54
	s_add_i32 s55, s45, 0xa000
	global_load_lds_dwordx4 v[8:9], off
	v_lshl_add_u64 v[8:9], v[14:15], 0, s[14:15]
	s_mov_b32 m0, s55
	v_lshl_add_u64 v[6:7], v[6:7], 0, s[14:15]
	global_load_lds_dwordx4 v[8:9], off
	s_add_i32 m0, s45, 0x1c000
	v_lshl_add_u64 v[4:5], v[4:5], 0, s[14:15]
	global_load_lds_dwordx4 v[6:7], off
	s_add_i32 m0, s45, 0x1e000
	s_lshr_b32 s1, s19, 26
	global_load_lds_dwordx4 v[4:5], off
	s_waitcnt vmcnt(8)
	s_barrier
	v_lshrrev_b32_e32 v4, 1, v2
	v_and_b32_e32 v208, 24, v4
	v_and_b32_e32 v22, 15, v2
	s_add_i32 s1, s18, s1
	v_lshlrev_b32_e32 v4, 1, v208
	v_lshlrev_b32_e32 v2, 2, v2
	s_ashr_i32 s53, s1, 6
	v_lshl_or_b32 v4, v22, 6, v4
	s_lshl_b32 s1, s16, 13
	v_and_b32_e32 v2, 32, v2
	v_bitop3_b32 v6, v4, s1, v2 bitop3:0xde
	s_lshl_b32 s1, s10, 5
	s_and_b32 s56, s1, 0x60
	s_lshl_b32 s1, s56, 7
	s_cmp_gt_i32 s18, 63
	v_lshl_or_b32 v1, s16, 6, v22
	s_cselect_b64 s[16:17], -1, 0
	s_add_i32 s57, s53, -2
	s_cmpk_lt_u32 s3, 0x100
	v_bitop3_b32 v199, v4, s1, v2 bitop3:0xde
	s_cselect_b64 s[18:19], -1, 0
	s_add_u32 s20, s80, 0x9900000
	v_add_u32_e32 v2, v18, v16
	s_addc_u32 s21, s81, 0
	v_add_lshl_u32 v2, v2, v17, 1
	s_add_u32 s22, s80, 0xb900000
	v_lshl_add_u64 v[212:213], s[8:9], 0, v[2:3]
	v_add_u32_e32 v2, v21, v19
	s_waitcnt vmcnt(6)
	s_addc_u32 s23, s81, 0
	v_add_lshl_u32 v2, v2, v20, 1
	v_mov_b32_e32 v4, v3
	v_mov_b32_e32 v5, v3
	s_add_u32 s24, s80, 0x4700000
	v_lshl_add_u64 v[214:215], s[8:9], 0, v[2:3]
	v_mov_b32_e32 v2, v3
	v_add_u32_e32 v228, 0, v6
	v_mov_b64_e32 v[8:9], v[4:5]
	v_mov_b64_e32 v[12:13], v[4:5]
	v_mov_b64_e32 v[16:17], v[4:5]
	v_mov_b64_e32 v[20:21], v[4:5]
	v_mov_b64_e32 v[24:25], v[4:5]
	v_mov_b64_e32 v[28:29], v[4:5]
	v_mov_b64_e32 v[32:33], v[4:5]
	v_mov_b64_e32 v[36:37], v[4:5]
	v_mov_b64_e32 v[40:41], v[4:5]
	v_mov_b64_e32 v[44:45], v[4:5]
	v_mov_b64_e32 v[48:49], v[4:5]
	v_mov_b64_e32 v[52:53], v[4:5]
	v_mov_b64_e32 v[56:57], v[4:5]
	v_mov_b64_e32 v[60:61], v[4:5]
	v_mov_b64_e32 v[64:65], v[4:5]
	v_mov_b64_e32 v[68:69], v[4:5]
	v_mov_b64_e32 v[72:73], v[4:5]
	v_mov_b64_e32 v[76:77], v[4:5]
	v_mov_b64_e32 v[80:81], v[4:5]
	v_mov_b64_e32 v[84:85], v[4:5]
	v_mov_b64_e32 v[88:89], v[4:5]
	v_mov_b64_e32 v[92:93], v[4:5]
	v_mov_b64_e32 v[96:97], v[4:5]
	v_mov_b64_e32 v[100:101], v[4:5]
	v_mov_b64_e32 v[104:105], v[4:5]
	v_mov_b64_e32 v[108:109], v[4:5]
	v_mov_b64_e32 v[112:113], v[4:5]
	v_mov_b64_e32 v[116:117], v[4:5]
	v_mov_b64_e32 v[120:121], v[4:5]
	v_mov_b64_e32 v[124:125], v[4:5]
	v_mov_b64_e32 v[128:129], v[4:5]
	s_waitcnt lgkmcnt(0)
	v_mov_b64_e32 v[132:133], v[4:5]
	s_addc_u32 s25, s81, 0
	v_or_b32_e32 v210, s56, v208
	v_or_b32_e32 v209, 16, v1
	v_or_b32_e32 v211, 32, v1
	v_or_b32_e32 v224, 48, v1
	v_add_u32_e32 v225, 0x90, v1
	v_add_u32_e32 v226, 0xa0, v1
	v_add_u32_e32 v227, 0xb0, v1
	s_add_i32 s58, 0, 0x10000
	s_add_i32 s59, 0, 0x14000
	v_mov_b64_e32 v[6:7], v[2:3]
	v_mov_b64_e32 v[10:11], v[2:3]
	v_mov_b64_e32 v[14:15], v[2:3]
	v_mov_b64_e32 v[18:19], v[2:3]
	v_mov_b64_e32 v[22:23], v[2:3]
	v_mov_b64_e32 v[26:27], v[2:3]
	v_mov_b64_e32 v[30:31], v[2:3]
	v_mov_b64_e32 v[34:35], v[2:3]
	v_mov_b64_e32 v[38:39], v[2:3]
	v_mov_b64_e32 v[42:43], v[2:3]
	v_mov_b64_e32 v[46:47], v[2:3]
	v_mov_b64_e32 v[50:51], v[2:3]
	v_mov_b64_e32 v[54:55], v[2:3]
	v_mov_b64_e32 v[58:59], v[2:3]
	v_mov_b64_e32 v[62:63], v[2:3]
	v_mov_b64_e32 v[66:67], v[2:3]
	v_mov_b64_e32 v[70:71], v[2:3]
	v_mov_b64_e32 v[74:75], v[2:3]
	v_mov_b64_e32 v[78:79], v[2:3]
	v_mov_b64_e32 v[82:83], v[2:3]
	v_mov_b64_e32 v[86:87], v[2:3]
	v_mov_b64_e32 v[90:91], v[2:3]
	v_mov_b64_e32 v[94:95], v[2:3]
	v_mov_b64_e32 v[98:99], v[2:3]
	v_mov_b64_e32 v[102:103], v[2:3]
	v_mov_b64_e32 v[106:107], v[2:3]
	v_mov_b64_e32 v[110:111], v[2:3]
	v_mov_b64_e32 v[114:115], v[2:3]
	v_mov_b64_e32 v[118:119], v[2:3]
	v_mov_b64_e32 v[122:123], v[2:3]
	v_mov_b64_e32 v[126:127], v[2:3]
	v_mov_b64_e32 v[130:131], v[2:3]
	s_mov_b32 s5, 0
	s_mov_b32 s60, 0
	s_barrier
	s_branch .LBB0_1983

.LBB0_2153:
	s_mov_b64 s[20:21], 0x80
	s_add_i32 m0, s3, 0x18000
	v_lshl_add_u64 v[10:11], v[10:11], 0, s[20:21]
	global_load_lds_dwordx4 v[10:11], off
	v_lshl_add_u64 v[6:7], v[6:7], 0, s[20:21]
	s_add_i32 m0, s3, 0x1a000
	s_add_i32 s50, s3, 0x8000
	global_load_lds_dwordx4 v[6:7], off
	v_lshl_add_u64 v[6:7], v[8:9], 0, s[20:21]
	s_mov_b32 m0, s50
	s_add_i32 s51, s3, 0xa000
	global_load_lds_dwordx4 v[6:7], off
	v_lshl_add_u64 v[6:7], v[12:13], 0, s[20:21]
	s_mov_b32 m0, s51
	v_lshl_add_u64 v[4:5], v[4:5], 0, s[20:21]
	global_load_lds_dwordx4 v[6:7], off
	s_add_i32 m0, s3, 0x1c000
	v_lshl_add_u64 v[2:3], v[2:3], 0, s[20:21]
	global_load_lds_dwordx4 v[4:5], off
	s_add_i32 m0, s3, 0x1e000
	s_and_b32 s52, s0, 3
	global_load_lds_dwordx4 v[2:3], off
	s_waitcnt vmcnt(8)
	s_barrier
	v_bfe_u32 v2, v14, 4, 2
	v_and_b32_e32 v3, 15, v14
	s_lshr_b32 s0, s23, 26
	v_lshlrev_b32_e32 v5, 4, v2
	s_add_i32 s0, s22, s0
	v_lshl_or_b32 v1, s1, 6, v3
	v_lshl_or_b32 v3, v3, 6, v5
	v_lshlrev_b32_e32 v5, 2, v14
	s_ashr_i32 s53, s0, 6
	s_lshl_b32 s0, s1, 13
	v_and_b32_e32 v5, 32, v5
	v_bitop3_b32 v6, v3, s0, v5 bitop3:0xde
	s_lshl_b32 s0, s52, 12
	s_cmp_gt_i32 s22, 63
	s_cselect_b64 s[26:27], -1, 0
	s_add_i32 s54, s53, -2
	s_cmpk_lt_u32 s4, 0x100
	v_bitop3_b32 v199, v3, s0, v5 bitop3:0xde
	s_mov_b32 s0, s22
	s_cselect_b64 s[22:23], -1, 0
	s_lshl_b32 s4, s52, 7
	v_writelane_b32 v251, s0, 5
	s_add_u32 s4, s56, s4
	v_lshlrev_b32_e32 v4, 3, v2
	v_writelane_b32 v251, s1, 6
	v_cmp_eq_u32_e64 s[0:1], 0, v2
	s_addc_u32 s5, s57, 0
	v_lshlrev_b32_e32 v204, 5, v2
	v_add_u32_e32 v2, v17, v15
	v_lshl_add_u64 v[208:209], s[4:5], 0, v[204:205]
	v_add_lshl_u32 v204, v2, v16, 1
	v_add_u32_e32 v2, v20, v18
	s_waitcnt vmcnt(6)
	s_add_u32 s24, s80, 0x1280000
	v_lshl_add_u64 v[210:211], s[14:15], 0, v[204:205]
	v_add_lshl_u32 v204, v2, v19, 1
	v_cndmask_b32_e64 v2, 0, 1, s[26:27]
	v_lshl_or_b32 v206, s52, 5, v4
	s_addc_u32 s25, s81, 0
	v_cmp_ne_u32_e64 s[4:5], 1, v2
	s_add_i32 s55, 0, 0x10000
	s_add_i32 s56, 0, 0x14000
	v_mbcnt_lo_u32_b32 v2, -1, 0
	v_or_b32_e32 v207, 16, v1
	v_or_b32_e32 v218, 32, v1
	v_or_b32_e32 v219, 48, v1
	v_lshl_add_u64 v[212:213], s[14:15], 0, v[204:205]
	v_add_u32_e32 v220, s55, v199
	v_add_u32_e32 v221, s56, v199
	v_add_u32_e32 v222, 0, v6
	s_mov_b64 s[26:27], 0x1102000
	s_mov_b32 s57, 0x1102000
	v_mbcnt_hi_u32_b32 v223, -1, v2
	v_lshlrev_b32_e32 v204, 2, v206
	s_mov_b32 s58, 0
	s_barrier
	s_branch .LBB0_2156

.LBB0_2188:
	s_mov_b64 s[16:17], 0x80
	s_add_i32 m0, s40, 0x18000
	v_lshl_add_u64 v[12:13], v[12:13], 0, s[16:17]
	global_load_lds_dwordx4 v[12:13], off
	v_lshl_add_u64 v[8:9], v[8:9], 0, s[16:17]
	s_add_i32 m0, s40, 0x1a000
	s_add_i32 s49, s40, 0x8000
	global_load_lds_dwordx4 v[8:9], off
	v_lshl_add_u64 v[8:9], v[10:11], 0, s[16:17]
	s_mov_b32 m0, s49
	s_add_i32 s50, s40, 0xa000
	global_load_lds_dwordx4 v[8:9], off
	v_lshl_add_u64 v[6:7], v[6:7], 0, s[16:17]
	s_mov_b32 m0, s50
	v_lshl_add_u64 v[4:5], v[4:5], 0, s[16:17]
	global_load_lds_dwordx4 v[6:7], off
	s_add_i32 m0, s40, 0x1c000
	v_lshl_add_u64 v[2:3], v[2:3], 0, s[16:17]
	global_load_lds_dwordx4 v[4:5], off
	s_add_i32 m0, s40, 0x1e000
	s_sext_i32_i8 s5, s18
	global_load_lds_dwordx4 v[2:3], off
	s_waitcnt vmcnt(8)
	s_barrier
	s_lshr_b32 s18, s23, 26
	v_and_b32_e32 v1, 15, v0
	s_add_i32 s18, s22, s18
	v_and_b32_e32 v2, 48, v0
	v_lshlrev_b32_e32 v3, 2, v0
	s_and_b32 s42, s3, 3
	s_ashr_i32 s51, s18, 6
	s_lshl_b32 s18, s38, 13
	v_lshl_or_b32 v2, v1, 6, v2
	v_and_b32_e32 v3, 32, v3
	v_bitop3_b32 v4, v2, s18, v3 bitop3:0xde
	s_lshl_b32 s18, s42, 12
	v_bitop3_b32 v146, v2, s18, v3 bitop3:0xde
	v_add_u32_e32 v2, v19, v17
	v_add_lshl_u32 v2, v2, v18, 1
	v_mov_b32_e32 v3, v102
	v_lshl_add_u64 v[142:143], s[0:1], 0, v[2:3]
	v_add_u32_e32 v2, v16, v14
	s_lshl_b32 s48, s38, 6
	s_waitcnt vmcnt(6)
	v_add_lshl_u32 v2, v2, v15, 1
	v_mov_b32_e32 v103, v102
	v_mov_b32_e32 v104, v102
	v_mov_b32_e32 v105, v102
	s_cmp_gt_i32 s22, 63
	v_lshl_add_u64 v[144:145], s[0:1], 0, v[2:3]
	v_add_u32_e32 v147, 0, v4
	v_mov_b64_e32 v[2:3], v[102:103]
	v_mov_b64_e32 v[6:7], v[102:103]
	v_mov_b64_e32 v[18:19], v[102:103]
	v_mov_b64_e32 v[22:23], v[102:103]
	v_mov_b64_e32 v[34:35], v[102:103]
	v_mov_b64_e32 v[38:39], v[102:103]
	v_mov_b64_e32 v[50:51], v[102:103]
	v_mov_b64_e32 v[54:55], v[102:103]
	v_mov_b64_e32 v[10:11], v[102:103]
	v_mov_b64_e32 v[14:15], v[102:103]
	v_mov_b64_e32 v[26:27], v[102:103]
	v_mov_b64_e32 v[30:31], v[102:103]
	v_mov_b64_e32 v[42:43], v[102:103]
	v_mov_b64_e32 v[46:47], v[102:103]
	v_mov_b64_e32 v[58:59], v[102:103]
	v_mov_b64_e32 v[62:63], v[102:103]
	v_mov_b64_e32 v[66:67], v[102:103]
	v_mov_b64_e32 v[70:71], v[102:103]
	v_mov_b64_e32 v[82:83], v[102:103]
	v_mov_b64_e32 v[86:87], v[102:103]
	v_mov_b64_e32 v[98:99], v[102:103]
	v_mov_b64_e32 v[108:109], v[104:105]
	v_mov_b64_e32 v[120:121], v[104:105]
	v_mov_b64_e32 v[124:125], v[104:105]
	v_mov_b64_e32 v[74:75], v[102:103]
	v_mov_b64_e32 v[78:79], v[102:103]
	v_mov_b64_e32 v[90:91], v[102:103]
	v_mov_b64_e32 v[94:95], v[102:103]
	v_mov_b64_e32 v[112:113], v[104:105]
	v_mov_b64_e32 v[116:117], v[104:105]
	v_mov_b64_e32 v[128:129], v[104:105]
	v_mov_b64_e32 v[132:133], v[104:105]
	v_or_b32_e32 v199, s48, v1
	s_cselect_b64 s[18:19], -1, 0
	s_add_i32 s52, s51, -2
	s_mov_b32 s57, 0
	s_add_i32 s53, 0, 0x10000
	s_add_i32 s54, 0, 0x14000
	s_add_i32 s55, s40, 0xc000
	s_add_i32 s56, s40, 0xe000
	v_mov_b64_e32 v[4:5], v[104:105]
	v_mov_b64_e32 v[8:9], v[104:105]
	v_mov_b64_e32 v[20:21], v[104:105]
	v_mov_b64_e32 v[24:25], v[104:105]
	v_mov_b64_e32 v[36:37], v[104:105]
	v_mov_b64_e32 v[40:41], v[104:105]
	v_mov_b64_e32 v[52:53], v[104:105]
	v_mov_b64_e32 v[56:57], v[104:105]
	v_mov_b64_e32 v[12:13], v[104:105]
	v_mov_b64_e32 v[16:17], v[104:105]
	v_mov_b64_e32 v[28:29], v[104:105]
	v_mov_b64_e32 v[32:33], v[104:105]
	v_mov_b64_e32 v[44:45], v[104:105]
	v_mov_b64_e32 v[48:49], v[104:105]
	v_mov_b64_e32 v[60:61], v[104:105]
	v_mov_b64_e32 v[64:65], v[104:105]
	v_mov_b64_e32 v[68:69], v[104:105]
	v_mov_b64_e32 v[72:73], v[104:105]
	v_mov_b64_e32 v[84:85], v[104:105]
	v_mov_b64_e32 v[88:89], v[104:105]
	v_mov_b64_e32 v[100:101], v[104:105]
	v_mov_b64_e32 v[106:107], v[102:103]
	v_mov_b64_e32 v[118:119], v[102:103]
	v_mov_b64_e32 v[122:123], v[102:103]
	v_mov_b64_e32 v[76:77], v[104:105]
	v_mov_b64_e32 v[80:81], v[104:105]
	v_mov_b64_e32 v[92:93], v[104:105]
	v_mov_b64_e32 v[96:97], v[104:105]
	v_mov_b64_e32 v[110:111], v[102:103]
	v_mov_b64_e32 v[114:115], v[102:103]
	v_mov_b64_e32 v[126:127], v[102:103]
	v_mov_b64_e32 v[130:131], v[102:103]
	s_barrier
	s_branch .LBB0_2190
